# plus static s_setprio 1 for waves 0-3 in windowed attention units
# speedup vs baseline: 1.0026x; 1.0006x over previous
; __device__ __forceinline__ unsigned cvtpk(float lo, float hi) { f32x2_t v = {lo, hi}; bf16x2_t b = __builtin_convertvector(v, bf16x2_t); return __builtin_bit_cast(unsigned, b); }
; __device__ __forceinline__ void attn_global(LAS unsigned char* lds, const bf16_t* __restrict__ PROJ, const bf16_t* __restrict__ VT, bf16_t* __restrict__ AO,
;                                             int rowbase, int S, int hq, int q0, float bound2) {
;     ...
;     float lsum = 0.f;
; #pragma unroll
;     for (int i = 0; i < 16; ++i) lsum += ls[i];
;     const float inv = 1.0f / (lsum + __shfl_xor(lsum, 32));
;     bf16_t* op = AO + (size_t)(rowbase + qw + r32) * PITCH_O + ocol + 4 * hi;
; #pragma unroll
;     for (int g4 = 0; g4 < 4; ++g4) {
;         u32x2 w0, w1;
;         w0.x = cvtpk(o0[4 * g4] * inv, o0[4 * g4 + 1] * inv); w0.y = cvtpk(o0[4 * g4 + 2] * inv, o0[4 * g4 + 3] * inv);
;         w1.x = cvtpk(o1[4 * g4] * inv, o1[4 * g4 + 1] * inv); w1.y = cvtpk(o1[4 * g4 + 2] * inv, o1[4 * g4 + 3] * inv);
;         *(u32x2*)(op + 8 * g4) = w0; *(u32x2*)(op + 32 + 8 * g4) = w1;
;     }
; __device__ __forceinline__ void attn_win(LAS unsigned char* lds, const bf16_t* __restrict__ PROJ, const bf16_t* __restrict__ VT, bf16_t* __restrict__ AO, ...
;     ...
;     const float lt = l + __shfl_xor(l, 32);
;     const float inv = 1.0f / lt;
;     bf16_t* op = AO + (size_t)(rowbase + qw + r32) * PITCH_O + ocol + 4 * hi;
; #pragma unroll
;     for (int g4 = 0; g4 < 4; ++g4) {
;         u32x2 w0, w1;
;         w0.x = cvtpk(o0[4 * g4] * inv, o0[4 * g4 + 1] * inv); w0.y = cvtpk(o0[4 * g4 + 2] * inv, o0[4 * g4 + 3] * inv);
;         w1.x = cvtpk(o1[4 * g4] * inv, o1[4 * g4 + 1] * inv); w1.y = cvtpk(o1[4 * g4 + 2] * inv, o1[4 * g4 + 3] * inv);
;         *(u32x2*)(op + 8 * g4) = w0; *(u32x2*)(op + 32 + 8 * g4) = w1;
;     }
.LBB0_203:
	s_setprio 0
	s_waitcnt lgkmcnt(0)
	v_add_f32_e32 v32, v94, v32
	v_div_scale_f32 v33, s[8:9], v32, v32, 1.0
	v_rcp_f32_e32 v34, v33
	v_div_scale_f32 v35, vcc, 1.0, v32, 1.0
	v_lshlrev_b32_e32 v150, 3, v167
	v_fma_f32 v36, -v33, v34, 1.0
	v_fmac_f32_e32 v34, v36, v34
	v_mul_f32_e32 v36, v35, v34
	v_fma_f32 v37, -v33, v36, v35
	v_fmac_f32_e32 v36, v37, v34
	v_fma_f32 v33, -v33, v36, v35
	v_div_fmas_f32 v33, v33, v34, v36
	v_div_fixup_f32 v32, v33, v32, 1.0
	v_lshlrev_b64 v[34:35], 11, v[156:157]
	v_lshl_add_u64 v[34:35], s[16:17], 0, v[34:35]
	v_pk_mul_f32 v[0:1], v[0:1], v[32:33] op_sel_hi:[1,0]
	v_pk_mul_f32 v[2:3], v[2:3], v[32:33] op_sel_hi:[1,0]
	v_pk_mul_f32 v[4:5], v[4:5], v[32:33] op_sel_hi:[1,0]
	v_pk_mul_f32 v[6:7], v[6:7], v[32:33] op_sel_hi:[1,0]
	v_pk_mul_f32 v[8:9], v[8:9], v[32:33] op_sel_hi:[1,0]
	v_pk_mul_f32 v[10:11], v[10:11], v[32:33] op_sel_hi:[1,0]
	v_pk_mul_f32 v[12:13], v[12:13], v[32:33] op_sel_hi:[1,0]
	v_pk_mul_f32 v[14:15], v[14:15], v[32:33] op_sel_hi:[1,0]
	v_pk_mul_f32 v[16:17], v[16:17], v[32:33] op_sel_hi:[1,0]
	v_pk_mul_f32 v[18:19], v[18:19], v[32:33] op_sel_hi:[1,0]
	v_pk_mul_f32 v[20:21], v[20:21], v[32:33] op_sel_hi:[1,0]
	v_pk_mul_f32 v[22:23], v[22:23], v[32:33] op_sel_hi:[1,0]
	v_pk_mul_f32 v[24:25], v[24:25], v[32:33] op_sel_hi:[1,0]
	v_pk_mul_f32 v[26:27], v[26:27], v[32:33] op_sel_hi:[1,0]
	v_pk_mul_f32 v[28:29], v[28:29], v[32:33] op_sel_hi:[1,0]
	v_pk_mul_f32 v[30:31], v[30:31], v[32:33] op_sel_hi:[1,0]
	v_lshl_add_u64 v[34:35], s[6:7], 1, v[34:35]
	v_lshl_add_u64 v[34:35], v[34:35], 0, v[150:151]
	v_lshl_add_u64 v[34:35], v[34:35], 0, v[150:151]
	v_cvt_pk_bf16_f32 v0, v0, v1
	v_cvt_pk_bf16_f32 v1, v2, v3
	v_cvt_pk_bf16_f32 v2, v4, v5
	v_cvt_pk_bf16_f32 v3, v6, v7
	v_cvt_pk_bf16_f32 v4, v8, v9
	v_cvt_pk_bf16_f32 v5, v10, v11
	v_cvt_pk_bf16_f32 v6, v12, v13
	v_cvt_pk_bf16_f32 v7, v14, v15
	v_cvt_pk_bf16_f32 v16, v16, v17
	v_cvt_pk_bf16_f32 v17, v18, v19
	v_cvt_pk_bf16_f32 v18, v20, v21
	v_cvt_pk_bf16_f32 v19, v22, v23
	v_cvt_pk_bf16_f32 v20, v24, v25
	v_cvt_pk_bf16_f32 v21, v26, v27
	v_cvt_pk_bf16_f32 v22, v28, v29
	v_cvt_pk_bf16_f32 v23, v30, v31
	s_add_i32 s75, s75, s47
	s_nop 1
	v_permlane32_swap_b32_e32 v0, v2
	v_permlane32_swap_b32_e32 v1, v3
	v_permlane32_swap_b32_e32 v4, v6
	v_permlane32_swap_b32_e32 v5, v7
	v_permlane32_swap_b32_e32 v16, v18
	v_permlane32_swap_b32_e32 v17, v19
	v_permlane32_swap_b32_e32 v20, v22
	v_permlane32_swap_b32_e32 v21, v23
	s_cmpk_gt_i32 s75, 0xfff
	global_store_dwordx4 v[34:35], v[0:3], off
	global_store_dwordx4 v[34:35], v[4:7], off offset:32
	global_store_dwordx4 v[34:35], v[16:19], off offset:64
	global_store_dwordx4 v[34:35], v[20:23], off offset:96
	s_cbranch_scc1 .LBB0_270

; #define LAS __attribute__((address_space(3)))
; __device__ __forceinline__ void attn_win(LAS unsigned char* lds, const bf16_t* __restrict__ PROJ, const bf16_t* __restrict__ VT, bf16_t* __restrict__ AO, ...
;     ...
;     LAS float* lut4 = (LAS float*)(lds + OFF_LUT);
;     for (int i = tid; i < 4 * 452; i += 512) lut4[i] = lut_g[kvh * 4 * 452 + i];
;     const LAS float* lut = lut4 + (wid >> 1) * 452;
;     const float sink2 = sinkp[hq] * LOG2E_F;
;     const int qw = q0 + (wid & 1) * 32;
;     const bf16_t* qp = PROJ + (size_t)(rowbase + qw + r32) * PITCH_P + qcol + hi * 8;
;     bf16x8 qf[4];
; #pragma unroll
;     for (int ds = 0; ds < 4; ++ds) qf[ds] = *(const bf16x8*)(qp + ds * 16);
;     u32x4 kreg = *(const u32x4*)(ksrc + (size_t)kt0 * 64 * PITCH_P);
;     u32x4 vreg = *(const u32x4*)(vsrc + (size_t)kt0 * 16384);
;     *(LAS u32x4*)(lds + kdst) = kreg;
;     *(LAS u32x2*)(lds + vdst) = (u32x2){vreg.x, vreg.y}; *(LAS u32x2*)(lds + vdst + 16) = (u32x2){vreg.z, vreg.w};
;     if (kt0 + 1 < kt1) { kreg = *(const u32x4*)(ksrc + (size_t)(kt0 + 1) * 64 * PITCH_P); vreg = *(const u32x4*)(vsrc + (size_t)(kt0 + 1) * 16384); }
;     float m = sink2, l = 0.5f;
;     f32x16 o0 = {}, o1 = {};
;     asm volatile("s_waitcnt lgkmcnt(0)\n\ts_barrier" ::: "memory");
.LBB0_260:
	s_or_b64 exec, exec, s[6:7]
	s_mov_b32 s100, s80
.Lwin_lutskip:
	v_readfirstlane_b32 s98, v171
	s_nop 3
	s_cmpk_lt_u32 s98, 0x100
	s_cbranch_scc0 .Lwin_noprio
	s_setprio 1
.Lwin_noprio:
	s_lshl_b32 s30, s81, 6
	s_add_i32 s7, s30, 0xc0
	s_lshl_b32 s6, s80, 2
	s_ashr_i32 s11, s13, 7
	s_min_u32 s7, s7, s79
	v_ashrrev_i32_e32 v2, 3, v0
	s_add_i32 s64, s11, s6
	v_sub_u32_e64 v16, s30, v184 clamp
	s_lshr_b32 s9, s7, 6
	v_add_u32_e32 v3, s78, v2
	v_mov_b64_e32 v[6:7], s[48:49]
	s_lshl_b32 s7, s78, 2
	s_lshl_b32 s31, s80, 6
	v_readfirstlane_b32 s8, v16
	v_mad_i64_i32 v[4:5], s[66:67], v3, s92, v[6:7]
	s_and_b32 s7, s7, 0x7c000
	s_ashr_i32 s65, s64, 31
	s_lshl_b32 s6, s64, 6
	s_lshr_b32 s8, s8, 6
	s_lshl_b32 s14, s80, 7
	s_or_b32 s66, s7, s31
	s_lshl_b64 s[64:65], s[64:65], 2
	s_add_u32 s64, s69, s64
	s_mov_b32 s67, s15
	v_ashrrev_i32_e32 v3, 31, v2
	s_addc_u32 s65, s74, s65
	s_lshr_b32 s7, s13, 1
	v_and_b32_e32 v1, 31, v0
	v_lshlrev_b32_e32 v17, 4, v0
	v_lshl_add_u64 v[10:11], v[2:3], 0, s[66:67]
	s_and_b32 s7, s7, 32
	v_lshl_add_u64 v[8:9], v[4:5], 0, s[14:15]
	v_and_b32_e32 v4, 0x70, v17
	v_mov_b32_e32 v5, v151
	v_lshlrev_b64 v[10:11], 7, v[10:11]
	s_or_b32 s12, s7, s30
	v_or_b32_e32 v12, s78, v1
	v_lshl_add_u64 v[8:9], v[8:9], 0, v[4:5]
	v_lshl_add_u64 v[10:11], s[50:51], 0, v[10:11]
	v_add_u32_e32 v150, s12, v12
	v_bfe_u32 v167, v0, 5, 1
	v_lshl_add_u64 v[10:11], v[10:11], 0, v[4:5]
	global_load_dword v5, v151, s[64:65]
	v_mad_u64_u32 v[6:7], s[64:65], v150, s92, v[6:7]
	s_ashr_i32 s7, s6, 31
	v_mad_u64_u32 v[14:15], s[64:65], s8, v185, v[8:9]
	v_lshl_add_u64 v[12:13], s[6:7], 1, v[6:7]
	v_lshlrev_b32_e32 v6, 4, v167
	v_mov_b32_e32 v7, v151
	s_lshl_b32 s64, s8, 15
	s_mov_b32 s65, s15
	v_lshl_add_u64 v[12:13], v[12:13], 0, v[6:7]
	global_load_dwordx4 v[76:79], v[14:15], off offset:2048
	global_load_dwordx4 v[64:67], v[12:13], off
	global_load_dwordx4 v[68:71], v[12:13], off offset:32
	v_lshl_add_u64 v[14:15], v[10:11], 0, s[64:65]
	global_load_dwordx4 v[84:87], v[14:15], off
	global_load_dwordx4 v[72:75], v[12:13], off offset:64
	global_load_dwordx4 v[80:83], v[12:13], off offset:96
	s_movk_i32 s10, 0x90
	v_lshlrev_b32_e32 v0, 3, v0
	v_mul_lo_u32 v7, v2, s10
	v_and_b32_e32 v12, 0x60, v17
	v_and_or_b32 v0, v0, 8, v7
	v_add_u32_e32 v93, v0, v12
	v_add_u32_e32 v92, v7, v4
	v_add_u32_e32 v0, 0, v93
	s_add_i32 s64, s8, 1
	v_readfirstlane_b32 s10, v16
	v_add_u32_e32 v7, 0, v92
	v_add_u32_e32 v0, 0x4800, v0
	s_cmp_lt_u32 s64, s9
	s_waitcnt vmcnt(5)
	ds_write_b128 v7, v[76:79]
	s_waitcnt vmcnt(2)
	ds_write2_b64 v0, v[84:85], v[86:87] offset1:2
	s_cbranch_scc0 .LBB0_262
	v_mad_u64_u32 v[8:9], s[66:67], s64, v185, v[8:9]
	s_lshl_b32 s64, s64, 15
	s_mov_b32 s65, s15
	v_lshl_add_u64 v[10:11], v[10:11], 0, s[64:65]
	global_load_dwordx4 v[76:79], v[8:9], off offset:2048
	global_load_dwordx4 v[84:87], v[10:11], off
